# K-loop barrier hand-off trimmed (priority raised before the barrier, redundant lgkmcnt wait dropped, priority drop after the post-MFMA barrier) on top of v87
# speedup vs baseline: 1.0012x; 1.0012x over previous
; #define PG8_LDA(dst, b, h) do { _Pragma("unroll") for (int m = 0; m < 4; ++m) _Pragma("unroll") for (int k = 0; k < 2; ++k) dst[m][k] = *(const LAS bf16x8*)(lds + PG8_SA(b, h) + aoff + m * 2048 + k * 1024); } while (0)
; #define PG8_LDB(dst, b, h) do { _Pragma("unroll") for (int n = 0; n < 2; ++n) _Pragma("unroll") for (int k = 0; k < 2; ++k) dst[n][k] = *(const LAS bf16x8*)(lds + PG8_SB(b, h) + boff + n * 2048 + k * 1024); } while (0)
; #define PG8_MMA(ai, bj, At, Bt) do { __builtin_amdgcn_s_setprio(1); _Pragma("unroll") for (int m = 0; m < 4; ++m) _Pragma("unroll") for (int n = 0; n < 2; ++n) _Pragma("unroll") for (int k = 0; k < 2; ++k) \
;         acc[ai][bj][m][n] = __builtin_amdgcn_mfma_f32_16x16x32_bf16(Bt[n][k], At[m][k], acc[ai][bj][m][n], 0, 0, 0); __builtin_amdgcn_s_setprio(0); } while (0)
; #define PG8_WAIT_V(n) asm volatile("s_waitcnt vmcnt(" #n ")" ::: "memory")
; #define PG8_WAIT_L(n) asm volatile("s_waitcnt lgkmcnt(" #n ")" ::: "memory")
; #define PG8_BAR __builtin_amdgcn_s_barrier()
; #define PG8_SCHED __builtin_amdgcn_sched_barrier(0)
; #define PG8_STA(bufoff, gbase, ld) PG8_STAGE(bufoff, gbase, RA0 * (unsigned)(ld) + CC0, RA1 * (unsigned)(ld) + CC1)
; __device__ __forceinline__ void gemm_phase(LAS unsigned char* lds, const Sched& S, const Epi& E) {
;     ...
;         for (int t = 0; t < nt_main; t += 2) {
;             const bool last = (t == nt - 2);
;             const char* a1 = cA + (size_t)(t + 1) * kstep;
;             const char* a2 = last ? nA : cA + (size_t)(t + 2) * kstep; const char* b2 = last ? nB : cB + (size_t)(t + 2) * kstep;
;             const char* a3 = a2 + kstep; const char* b3 = b2 + kstep;
;             const int xlda = last ? nlda : lda, xldb = last ? nldb : ldb;
;             const size_t xhA = (size_t)HALF * xlda * 2, xhB = (size_t)HALF * xldb * 2;
;             PG8_LDB(B0, 0, 0); PG8_LDB(B1, 0, 1); PG8_SCHED; PG8_LDA(At, 0, 0); PG8_STA(PG8_SA(1, 1), a1 + hA, lda);
;             PG8_WAIT_V(8); PG8_WAIT_L(0); PG8_BAR; PG8_MMA(0, 0, At, B0); PG8_MMA(0, 1, At, B1); PG8_BAR; PG8_SCHED;
;             PG8_LDA(At, 0, 1); PG8_STB(PG8_SB(0, 0), b2, xldb); PG8_STB(PG8_SB(0, 1), b2 + xhB, xldb); PG8_STA(PG8_SA(0, 0), a2, xlda);
;             PG8_WAIT_V(8); PG8_WAIT_L(0); PG8_BAR; PG8_MMA(1, 0, At, B0); PG8_MMA(1, 1, At, B1); PG8_BAR; PG8_SCHED;
.LBB0_263:
	s_nop 0
	s_add_i32 s24, s8, 2
	s_add_u32 s26, vcc_lo, 0x80
	s_addc_u32 s9, vcc_hi, 0
	s_add_i32 s37, 0, 0x10000
	s_cmp_eq_u32 s21, s8
	s_cselect_b32 s9, s7, s9
	s_cselect_b32 s8, s6, s26
	s_cselect_b32 s92, s11, s61
	s_cselect_b32 s30, s22, s20
	v_add_u32_e32 v0, s37, v241
	s_cselect_b32 s29, s13, s72
	s_cselect_b32 s28, s12, s2
	s_add_i32 s57, 0, 0x14000
	ds_read_b128 v[134:137], v0
	ds_read_b128 v[138:141], v0 offset:1024
	ds_read_b128 v[142:145], v0 offset:2048
	ds_read_b128 v[146:149], v0 offset:3072
	v_add_u32_e32 v0, s57, v241
	ds_read_b128 v[150:153], v0
	ds_read_b128 v[154:157], v0 offset:1024
	ds_read_b128 v[158:161], v0 offset:2048
	ds_read_b128 v[162:165], v0 offset:3072
	s_mov_b32 s93, s31
	s_lshl_b64 s[26:27], s[30:31], 8
	v_add_u32_e32 v0, 0, v240
	v_lshl_add_u64 v[214:215], vcc, 0, v[130:131]
	s_add_i32 m0, s34, 0xc000
	ds_read_b128 v[166:169], v0
	ds_read_b128 v[170:173], v0 offset:1024
	ds_read_b128 v[174:177], v0 offset:2048
	ds_read_b128 v[178:181], v0 offset:3072
	ds_read_b128 v[182:185], v0 offset:4096
	ds_read_b128 v[186:189], v0 offset:5120
	ds_read_b128 v[190:193], v0 offset:6144
	ds_read_b128 v[210:213], v0 offset:7168
	global_load_lds_dwordx4 v[214:215], off
	v_lshl_add_u64 v[214:215], vcc, 0, v[132:133]
	s_add_i32 m0, s34, 0xe000
	s_nop 0
	global_load_lds_dwordx4 v[214:215], off
	s_waitcnt vmcnt(8)
	s_waitcnt lgkmcnt(0)
	s_setprio 1
	s_barrier
	v_mfma_f32_16x16x32_bf16 v[126:129], v[134:137], v[166:169], v[126:129]
	v_mfma_f32_16x16x32_bf16 v[122:125], v[142:145], v[166:169], v[122:125]
	v_mfma_f32_16x16x32_bf16 v[110:113], v[134:137], v[174:177], v[110:113]
	v_mfma_f32_16x16x32_bf16 v[106:109], v[142:145], v[174:177], v[106:109]
	v_mfma_f32_16x16x32_bf16 v[98:101], v[134:137], v[182:185], v[98:101]
	v_mfma_f32_16x16x32_bf16 v[90:93], v[142:145], v[182:185], v[90:93]
	v_mfma_f32_16x16x32_bf16 v[82:85], v[134:137], v[190:193], v[82:85]
	v_mfma_f32_16x16x32_bf16 v[74:77], v[142:145], v[190:193], v[74:77]
	v_mfma_f32_16x16x32_bf16 v[126:129], v[138:141], v[170:173], v[126:129]
	v_mfma_f32_16x16x32_bf16 v[122:125], v[146:149], v[170:173], v[122:125]
	v_mfma_f32_16x16x32_bf16 v[110:113], v[138:141], v[178:181], v[110:113]
	v_mfma_f32_16x16x32_bf16 v[106:109], v[146:149], v[178:181], v[106:109]
	v_mfma_f32_16x16x32_bf16 v[98:101], v[138:141], v[186:189], v[98:101]
	v_mfma_f32_16x16x32_bf16 v[90:93], v[146:149], v[186:189], v[90:93]
	v_mfma_f32_16x16x32_bf16 v[82:85], v[138:141], v[210:213], v[82:85]
	v_mfma_f32_16x16x32_bf16 v[74:77], v[146:149], v[210:213], v[74:77]
	s_setprio 0
	s_setprio 1
	v_mfma_f32_16x16x32_bf16 v[118:121], v[150:153], v[166:169], v[118:121]
	v_mfma_f32_16x16x32_bf16 v[114:117], v[158:161], v[166:169], v[114:117]
	v_mfma_f32_16x16x32_bf16 v[102:105], v[150:153], v[174:177], v[102:105]
	v_mfma_f32_16x16x32_bf16 v[94:97], v[158:161], v[174:177], v[94:97]
	v_mfma_f32_16x16x32_bf16 v[86:89], v[150:153], v[182:185], v[86:89]
	v_mfma_f32_16x16x32_bf16 v[78:81], v[158:161], v[182:185], v[78:81]
	v_mfma_f32_16x16x32_bf16 v[70:73], v[150:153], v[190:193], v[70:73]
	v_mfma_f32_16x16x32_bf16 v[66:69], v[158:161], v[190:193], v[66:69]
	v_mfma_f32_16x16x32_bf16 v[118:121], v[154:157], v[170:173], v[118:121]
	v_mfma_f32_16x16x32_bf16 v[114:117], v[162:165], v[170:173], v[114:117]
	v_mfma_f32_16x16x32_bf16 v[102:105], v[154:157], v[178:181], v[102:105]
	v_mfma_f32_16x16x32_bf16 v[94:97], v[162:165], v[178:181], v[94:97]
	v_mfma_f32_16x16x32_bf16 v[86:89], v[154:157], v[186:189], v[86:89]
	v_mfma_f32_16x16x32_bf16 v[78:81], v[162:165], v[186:189], v[78:81]
	v_mfma_f32_16x16x32_bf16 v[70:73], v[154:157], v[210:213], v[70:73]
	v_mfma_f32_16x16x32_bf16 v[66:69], v[162:165], v[210:213], v[66:69]
	s_barrier
	s_setprio 0
	s_nop 0
	s_add_i32 s37, s37, s25
	v_mad_u64_u32 v[214:215], s[80:81], s92, v237, v[194:195]
	s_mov_b32 m0, s37
	ds_read_b128 v[166:169], v0 offset:16384
	ds_read_b128 v[170:173], v0 offset:17408
	ds_read_b128 v[174:177], v0 offset:18432
	ds_read_b128 v[178:181], v0 offset:19456
	ds_read_b128 v[182:185], v0 offset:20480
	ds_read_b128 v[186:189], v0 offset:21504
	ds_read_b128 v[190:193], v0 offset:22528
	ds_read_b128 v[210:213], v0 offset:23552
	s_lshl_b64 s[74:75], s[92:93], 8
	global_load_lds_dwordx4 v214, s[28:29]
	s_add_i32 m0, s37, 0x2000
	s_add_u32 s74, s28, s74
	v_mad_u64_u32 v[216:217], s[80:81], s92, v238, v[196:197]
	s_addc_u32 s75, s29, s75
	s_add_i32 s37, s57, s25
	global_load_lds_dwordx4 v216, s[28:29]
	s_mov_b32 m0, s37
	v_mad_u64_u32 v[218:219], s[80:81], s30, v235, v[194:195]
	global_load_lds_dwordx4 v214, s[74:75]
	s_add_i32 m0, s37, 0x2000
	v_mad_u64_u32 v[220:221], s[80:81], s30, v236, v[196:197]
	global_load_lds_dwordx4 v216, s[74:75]
	s_mov_b32 m0, s34
	v_mov_b32_e32 v215, v1
	global_load_lds_dwordx4 v218, s[8:9]
	s_mov_b32 m0, s35
	v_mov_b32_e32 v217, v1
	global_load_lds_dwordx4 v220, s[8:9]
	v_mov_b32_e32 v219, v1
	v_mov_b32_e32 v221, v1
	v_lshl_add_u64 v[222:223], s[28:29], 0, v[214:215]
	v_lshl_add_u64 v[224:225], s[28:29], 0, v[216:217]
	v_lshl_add_u64 v[214:215], s[74:75], 0, v[214:215]
	v_lshl_add_u64 v[216:217], s[74:75], 0, v[216:217]
	v_lshl_add_u64 v[226:227], s[8:9], 0, v[218:219]
	v_lshl_add_u64 v[228:229], s[8:9], 0, v[220:221]
	s_waitcnt vmcnt(8)
	s_waitcnt lgkmcnt(0)
	s_setprio 1
	s_barrier
; #define PG8_LDA(dst, b, h) do { _Pragma("unroll") for (int m = 0; m < 4; ++m) _Pragma("unroll") for (int k = 0; k < 2; ++k) dst[m][k] = *(const LAS bf16x8*)(lds + PG8_SA(b, h) + aoff + m * 2048 + k * 1024); } while (0)
; #define PG8_LDB(dst, b, h) do { _Pragma("unroll") for (int n = 0; n < 2; ++n) _Pragma("unroll") for (int k = 0; k < 2; ++k) dst[n][k] = *(const LAS bf16x8*)(lds + PG8_SB(b, h) + boff + n * 2048 + k * 1024); } while (0)
; #define PG8_MMA(ai, bj, At, Bt) do { __builtin_amdgcn_s_setprio(1); _Pragma("unroll") for (int m = 0; m < 4; ++m) _Pragma("unroll") for (int n = 0; n < 2; ++n) _Pragma("unroll") for (int k = 0; k < 2; ++k) \
;         acc[ai][bj][m][n] = __builtin_amdgcn_mfma_f32_16x16x32_bf16(Bt[n][k], At[m][k], acc[ai][bj][m][n], 0, 0, 0); __builtin_amdgcn_s_setprio(0); } while (0)
; #define PG8_WAIT_V(n) asm volatile("s_waitcnt vmcnt(" #n ")" ::: "memory")
; #define PG8_WAIT_L(n) asm volatile("s_waitcnt lgkmcnt(" #n ")" ::: "memory")
; #define PG8_BAR __builtin_amdgcn_s_barrier()
; #define PG8_SCHED __builtin_amdgcn_sched_barrier(0)
; #define PG8_STA(bufoff, gbase, ld) PG8_STAGE(bufoff, gbase, RA0 * (unsigned)(ld) + CC0, RA1 * (unsigned)(ld) + CC1)
; __device__ __forceinline__ void gemm_phase(LAS unsigned char* lds, const Sched& S, const Epi& E) {
;     ...
;             PG8_WAIT_V(8); PG8_WAIT_L(0); PG8_BAR; PG8_MMA(1, 0, At, B0); PG8_MMA(1, 1, At, B1); PG8_BAR; PG8_SCHED;
;             PG8_LDB(B0, 1, 0); PG8_LDB(B1, 1, 1); PG8_SCHED; PG8_LDA(At, 1, 0); PG8_STA(PG8_SA(0, 1), a2 + xhA, xlda);
;             PG8_WAIT_V(8); PG8_WAIT_L(0); PG8_BAR; PG8_MMA(0, 0, At, B0); PG8_MMA(0, 1, At, B1); PG8_BAR; PG8_SCHED;
	v_mfma_f32_16x16x32_bf16 v[62:65], v[134:137], v[166:169], v[62:65]
	v_mfma_f32_16x16x32_bf16 v[58:61], v[142:145], v[166:169], v[58:61]
	v_mfma_f32_16x16x32_bf16 v[46:49], v[134:137], v[174:177], v[46:49]
	v_mfma_f32_16x16x32_bf16 v[42:45], v[142:145], v[174:177], v[42:45]
	v_mfma_f32_16x16x32_bf16 v[30:33], v[134:137], v[182:185], v[30:33]
	v_mfma_f32_16x16x32_bf16 v[26:29], v[142:145], v[182:185], v[26:29]
	v_mfma_f32_16x16x32_bf16 v[14:17], v[134:137], v[190:193], v[14:17]
	v_mfma_f32_16x16x32_bf16 v[10:13], v[142:145], v[190:193], v[10:13]
	v_mfma_f32_16x16x32_bf16 v[62:65], v[138:141], v[170:173], v[62:65]
	v_mfma_f32_16x16x32_bf16 v[58:61], v[146:149], v[170:173], v[58:61]
	v_mfma_f32_16x16x32_bf16 v[46:49], v[138:141], v[178:181], v[46:49]
	v_mfma_f32_16x16x32_bf16 v[42:45], v[146:149], v[178:181], v[42:45]
	v_mfma_f32_16x16x32_bf16 v[30:33], v[138:141], v[186:189], v[30:33]
	v_mfma_f32_16x16x32_bf16 v[26:29], v[146:149], v[186:189], v[26:29]
	v_mfma_f32_16x16x32_bf16 v[14:17], v[138:141], v[210:213], v[14:17]
	v_mfma_f32_16x16x32_bf16 v[10:13], v[146:149], v[210:213], v[10:13]
	s_setprio 0
	s_setprio 1
	v_mfma_f32_16x16x32_bf16 v[54:57], v[150:153], v[166:169], v[54:57]
	v_mfma_f32_16x16x32_bf16 v[50:53], v[158:161], v[166:169], v[50:53]
	v_mfma_f32_16x16x32_bf16 v[38:41], v[150:153], v[174:177], v[38:41]
	v_mfma_f32_16x16x32_bf16 v[34:37], v[158:161], v[174:177], v[34:37]
	v_mfma_f32_16x16x32_bf16 v[22:25], v[150:153], v[182:185], v[22:25]
	v_mfma_f32_16x16x32_bf16 v[18:21], v[158:161], v[182:185], v[18:21]
	v_mfma_f32_16x16x32_bf16 v[6:9], v[150:153], v[190:193], v[6:9]
	v_mfma_f32_16x16x32_bf16 v[2:5], v[158:161], v[190:193], v[2:5]
	v_mfma_f32_16x16x32_bf16 v[54:57], v[154:157], v[170:173], v[54:57]
	v_mfma_f32_16x16x32_bf16 v[50:53], v[162:165], v[170:173], v[50:53]
	v_mfma_f32_16x16x32_bf16 v[38:41], v[154:157], v[178:181], v[38:41]
	v_mfma_f32_16x16x32_bf16 v[34:37], v[162:165], v[178:181], v[34:37]
	v_mfma_f32_16x16x32_bf16 v[22:25], v[154:157], v[186:189], v[22:25]
	v_mfma_f32_16x16x32_bf16 v[18:21], v[162:165], v[186:189], v[18:21]
	v_mfma_f32_16x16x32_bf16 v[6:9], v[154:157], v[210:213], v[6:9]
	v_mfma_f32_16x16x32_bf16 v[2:5], v[162:165], v[210:213], v[2:5]
	s_barrier
	s_setprio 0
	s_nop 0
	s_add_i32 s28, 0, 0x18000
	s_add_i32 s29, 0, 0x1c000
	v_add_u32_e32 v146, s28, v241
	v_add_u32_e32 v162, s29, v241
	ds_read_b128 v[134:137], v146
	ds_read_b128 v[138:141], v146 offset:1024
	ds_read_b128 v[142:145], v146 offset:2048
	ds_read_b128 v[146:149], v146 offset:3072
	ds_read_b128 v[150:153], v162
	ds_read_b128 v[154:157], v162 offset:1024
	ds_read_b128 v[158:161], v162 offset:2048
	ds_read_b128 v[162:165], v162 offset:3072
	s_add_u32 s8, s8, s26
	s_addc_u32 s9, s9, s27
	s_mov_b32 m0, s39
	ds_read_b128 v[166:169], v0 offset:32768
	ds_read_b128 v[170:173], v0 offset:33792
	ds_read_b128 v[174:177], v0 offset:34816
	ds_read_b128 v[178:181], v0 offset:35840
	ds_read_b128 v[182:185], v0 offset:36864
	ds_read_b128 v[186:189], v0 offset:37888
	ds_read_b128 v[190:193], v0 offset:38912
	ds_read_b128 v[210:213], v0 offset:39936
	global_load_lds_dwordx4 v218, s[8:9]
	s_mov_b32 m0, s91
	s_nop 0
	global_load_lds_dwordx4 v220, s[8:9]
	s_waitcnt vmcnt(8)
	s_waitcnt lgkmcnt(0)
	s_setprio 1
	s_barrier
	v_mfma_f32_16x16x32_bf16 v[126:129], v[134:137], v[166:169], v[126:129]
	v_mfma_f32_16x16x32_bf16 v[122:125], v[142:145], v[166:169], v[122:125]
	v_mfma_f32_16x16x32_bf16 v[110:113], v[134:137], v[174:177], v[110:113]
	v_mfma_f32_16x16x32_bf16 v[106:109], v[142:145], v[174:177], v[106:109]
	v_mfma_f32_16x16x32_bf16 v[98:101], v[134:137], v[182:185], v[98:101]
	v_mfma_f32_16x16x32_bf16 v[90:93], v[142:145], v[182:185], v[90:93]
	v_mfma_f32_16x16x32_bf16 v[82:85], v[134:137], v[190:193], v[82:85]
	v_mfma_f32_16x16x32_bf16 v[74:77], v[142:145], v[190:193], v[74:77]
	v_mfma_f32_16x16x32_bf16 v[126:129], v[138:141], v[170:173], v[126:129]
	v_mfma_f32_16x16x32_bf16 v[122:125], v[146:149], v[170:173], v[122:125]
	v_mfma_f32_16x16x32_bf16 v[110:113], v[138:141], v[178:181], v[110:113]
	v_mfma_f32_16x16x32_bf16 v[106:109], v[146:149], v[178:181], v[106:109]
	v_mfma_f32_16x16x32_bf16 v[98:101], v[138:141], v[186:189], v[98:101]
	v_mfma_f32_16x16x32_bf16 v[90:93], v[146:149], v[186:189], v[90:93]
	v_mfma_f32_16x16x32_bf16 v[82:85], v[138:141], v[210:213], v[82:85]
	v_mfma_f32_16x16x32_bf16 v[74:77], v[146:149], v[210:213], v[74:77]
	s_setprio 0
	s_setprio 1
	v_mfma_f32_16x16x32_bf16 v[118:121], v[150:153], v[166:169], v[118:121]
	v_mfma_f32_16x16x32_bf16 v[114:117], v[158:161], v[166:169], v[114:117]
	v_mfma_f32_16x16x32_bf16 v[102:105], v[150:153], v[174:177], v[102:105]
	v_mfma_f32_16x16x32_bf16 v[94:97], v[158:161], v[174:177], v[94:97]
	v_mfma_f32_16x16x32_bf16 v[86:89], v[150:153], v[182:185], v[86:89]
	v_mfma_f32_16x16x32_bf16 v[78:81], v[158:161], v[182:185], v[78:81]
	v_mfma_f32_16x16x32_bf16 v[70:73], v[150:153], v[190:193], v[70:73]
	v_mfma_f32_16x16x32_bf16 v[66:69], v[158:161], v[190:193], v[66:69]
	v_mfma_f32_16x16x32_bf16 v[118:121], v[154:157], v[170:173], v[118:121]
	v_mfma_f32_16x16x32_bf16 v[114:117], v[162:165], v[170:173], v[114:117]
	v_mfma_f32_16x16x32_bf16 v[102:105], v[154:157], v[178:181], v[102:105]
	v_mfma_f32_16x16x32_bf16 v[94:97], v[162:165], v[178:181], v[94:97]
	v_mfma_f32_16x16x32_bf16 v[86:89], v[154:157], v[186:189], v[86:89]
	v_mfma_f32_16x16x32_bf16 v[78:81], v[162:165], v[186:189], v[78:81]
	v_mfma_f32_16x16x32_bf16 v[70:73], v[154:157], v[210:213], v[70:73]
	v_mfma_f32_16x16x32_bf16 v[66:69], v[162:165], v[210:213], v[66:69]
	s_barrier
; #define PG8_LDA(dst, b, h) do { _Pragma("unroll") for (int m = 0; m < 4; ++m) _Pragma("unroll") for (int k = 0; k < 2; ++k) dst[m][k] = *(const LAS bf16x8*)(lds + PG8_SA(b, h) + aoff + m * 2048 + k * 1024); } while (0)
; #define PG8_MMA(ai, bj, At, Bt) do { __builtin_amdgcn_s_setprio(1); _Pragma("unroll") for (int m = 0; m < 4; ++m) _Pragma("unroll") for (int n = 0; n < 2; ++n) _Pragma("unroll") for (int k = 0; k < 2; ++k) \
;         acc[ai][bj][m][n] = __builtin_amdgcn_mfma_f32_16x16x32_bf16(Bt[n][k], At[m][k], acc[ai][bj][m][n], 0, 0, 0); __builtin_amdgcn_s_setprio(0); } while (0)
; #define PG8_WAIT_V(n) asm volatile("s_waitcnt vmcnt(" #n ")" ::: "memory")
; #define PG8_WAIT_L(n) asm volatile("s_waitcnt lgkmcnt(" #n ")" ::: "memory")
; #define PG8_BAR __builtin_amdgcn_s_barrier()
; #define PG8_SCHED __builtin_amdgcn_sched_barrier(0)
; #define PG8_STA(bufoff, gbase, ld) PG8_STAGE(bufoff, gbase, RA0 * (unsigned)(ld) + CC0, RA1 * (unsigned)(ld) + CC1)
; #define PG8_STB(bufoff, gbase, ld) PG8_STAGE(bufoff, gbase, RB0 * (unsigned)(ld) + CC0, RB1 * (unsigned)(ld) + CC1)
; __device__ __forceinline__ void gemm_phase(LAS unsigned char* lds, const Sched& S, const Epi& E) {
;     ...
;         for (int t = 0; t < nt_main; t += 2) {
;     ...
;             PG8_LDA(At, 1, 1); PG8_STB(PG8_SB(1, 0), b3, xldb); PG8_STB(PG8_SB(1, 1), b3 + xhB, xldb); PG8_STA(PG8_SA(1, 0), a3, xlda);
;             PG8_WAIT_V(8); PG8_WAIT_L(0); PG8_BAR; PG8_MMA(1, 0, At, B0); PG8_MMA(1, 1, At, B1); PG8_BAR; PG8_SCHED;
	s_setprio 0
	s_nop 0
	s_add_i32 s8, s28, s25
	v_lshl_add_u64 v[218:219], v[222:223], 0, s[52:53]
	s_mov_b32 m0, s8
	ds_read_b128 v[166:169], v0 offset:49152
	ds_read_b128 v[170:173], v0 offset:50176
	ds_read_b128 v[174:177], v0 offset:51200
	ds_read_b128 v[178:181], v0 offset:52224
	ds_read_b128 v[182:185], v0 offset:53248
	ds_read_b128 v[186:189], v0 offset:54272
	ds_read_b128 v[190:193], v0 offset:55296
	ds_read_b128 v[210:213], v0 offset:56320
	global_load_lds_dwordx4 v[218:219], off
	v_lshl_add_u64 v[218:219], v[224:225], 0, s[52:53]
	s_add_i32 m0, s8, 0x2000
	s_add_i32 s8, s29, s25
	global_load_lds_dwordx4 v[218:219], off
	v_lshl_add_u64 v[214:215], v[214:215], 0, s[52:53]
	s_mov_b32 m0, s8
	s_nop 0
	global_load_lds_dwordx4 v[214:215], off
	v_lshl_add_u64 v[214:215], v[216:217], 0, s[52:53]
	s_add_i32 m0, s8, 0x2000
	s_nop 0
	global_load_lds_dwordx4 v[214:215], off
	v_lshl_add_u64 v[214:215], v[226:227], 0, s[52:53]
	s_mov_b32 m0, s90
	s_nop 0
	global_load_lds_dwordx4 v[214:215], off
	v_lshl_add_u64 v[214:215], v[228:229], 0, s[52:53]
	s_mov_b32 m0, s73
	s_nop 0
	global_load_lds_dwordx4 v[214:215], off
	s_nop 0
	s_waitcnt vmcnt(8)
	s_waitcnt lgkmcnt(0)
	s_setprio 1
	s_barrier
	v_mfma_f32_16x16x32_bf16 v[62:65], v[134:137], v[166:169], v[62:65]
	v_mfma_f32_16x16x32_bf16 v[58:61], v[142:145], v[166:169], v[58:61]
	v_mfma_f32_16x16x32_bf16 v[46:49], v[134:137], v[174:177], v[46:49]
	v_mfma_f32_16x16x32_bf16 v[42:45], v[142:145], v[174:177], v[42:45]
	v_mfma_f32_16x16x32_bf16 v[30:33], v[134:137], v[182:185], v[30:33]
	v_mfma_f32_16x16x32_bf16 v[26:29], v[142:145], v[182:185], v[26:29]
	v_mfma_f32_16x16x32_bf16 v[14:17], v[134:137], v[190:193], v[14:17]
	v_mfma_f32_16x16x32_bf16 v[10:13], v[142:145], v[190:193], v[10:13]
	v_mfma_f32_16x16x32_bf16 v[62:65], v[138:141], v[170:173], v[62:65]
	v_mfma_f32_16x16x32_bf16 v[58:61], v[146:149], v[170:173], v[58:61]
	v_mfma_f32_16x16x32_bf16 v[46:49], v[138:141], v[178:181], v[46:49]
	v_mfma_f32_16x16x32_bf16 v[42:45], v[146:149], v[178:181], v[42:45]
	v_mfma_f32_16x16x32_bf16 v[30:33], v[138:141], v[186:189], v[30:33]
	v_mfma_f32_16x16x32_bf16 v[26:29], v[146:149], v[186:189], v[26:29]
	v_mfma_f32_16x16x32_bf16 v[14:17], v[138:141], v[210:213], v[14:17]
	v_mfma_f32_16x16x32_bf16 v[10:13], v[146:149], v[210:213], v[10:13]
	s_setprio 0
	s_setprio 1
	v_mfma_f32_16x16x32_bf16 v[54:57], v[150:153], v[166:169], v[54:57]
	v_mfma_f32_16x16x32_bf16 v[50:53], v[158:161], v[166:169], v[50:53]
	v_mfma_f32_16x16x32_bf16 v[38:41], v[150:153], v[174:177], v[38:41]
	v_mfma_f32_16x16x32_bf16 v[34:37], v[158:161], v[174:177], v[34:37]
	v_mfma_f32_16x16x32_bf16 v[22:25], v[150:153], v[182:185], v[22:25]
	v_mfma_f32_16x16x32_bf16 v[18:21], v[158:161], v[182:185], v[18:21]
	v_mfma_f32_16x16x32_bf16 v[6:9], v[150:153], v[190:193], v[6:9]
	v_mfma_f32_16x16x32_bf16 v[2:5], v[158:161], v[190:193], v[2:5]
	v_mfma_f32_16x16x32_bf16 v[54:57], v[154:157], v[170:173], v[54:57]
	v_mfma_f32_16x16x32_bf16 v[50:53], v[162:165], v[170:173], v[50:53]
	v_mfma_f32_16x16x32_bf16 v[38:41], v[154:157], v[178:181], v[38:41]
	v_mfma_f32_16x16x32_bf16 v[34:37], v[162:165], v[178:181], v[34:37]
	v_mfma_f32_16x16x32_bf16 v[22:25], v[154:157], v[186:189], v[22:25]
	v_mfma_f32_16x16x32_bf16 v[18:21], v[162:165], v[186:189], v[18:21]
	v_mfma_f32_16x16x32_bf16 v[6:9], v[154:157], v[210:213], v[6:9]
	v_mfma_f32_16x16x32_bf16 v[2:5], v[162:165], v[210:213], v[2:5]
	s_barrier
	s_setprio 0
	s_add_u32 vcc_lo, vcc_lo, 0x100
	s_addc_u32 vcc_hi, vcc_hi, 0
	s_add_u32 s2, s2, 0x100
	s_addc_u32 s72, s72, 0
	s_cmp_ge_i32 s24, s68
	s_mov_b32 s8, s24
	s_cbranch_scc0 .LBB0_263
	s_nop 0
	s_mov_b32 s92, s3
	s_movk_i32 s93, 0x3fff
	s_movk_i32 s3, 0x2000
	s_and_b64 vcc, exec, s[44:45]
	s_cbranch_vccz .LBB0_266
